# keep_v13 plus grid barrier: non-leader workgroups poll the top-level arrival counter directly (skip the per-XCD generation word hop)
# speedup vs baseline: 1.0092x; 1.0092x over previous
.LBB0_173:
	s_lshl_b32 s8, s3, 8
	s_add_u32 s8, s40, s8
	s_addc_u32 s9, s41, 0
	v_mov_b32_e32 v2, 0x1000
	v_mov_b32_e32 v4, 1
	global_atomic_add v4, v2, v4, s[8:9] offset:1024 sc0
	v_cvt_f32_u32_e32 v2, v3
	v_sub_u32_e32 v5, 0, v3
	v_rcp_iflag_f32_e32 v2, v2
	s_nop 0
	v_mul_f32_e32 v2, 0x4f7ffffe, v2
	v_cvt_u32_f32_e32 v2, v2
	v_mul_lo_u32 v5, v5, v2
	v_mul_hi_u32 v5, v2, v5
	v_add_u32_e32 v2, v2, v5
	s_waitcnt vmcnt(0)
	v_mul_hi_u32 v2, v4, v2
	v_mul_lo_u32 v5, v2, v3
	v_sub_u32_e32 v5, v4, v5
	v_add_u32_e32 v6, 1, v2
	v_cmp_ge_u32_e32 vcc, v5, v3
	v_add_u32_e32 v4, 1, v4
	s_nop 0
	v_cndmask_b32_e32 v2, v2, v6, vcc
	v_sub_u32_e32 v6, v5, v3
	v_cndmask_b32_e32 v5, v5, v6, vcc
	v_add_u32_e32 v6, 1, v2
	v_cmp_ge_u32_e32 vcc, v5, v3
	s_nop 1
	v_cndmask_b32_e32 v2, v2, v6, vcc
	v_mul_lo_u32 v5, v3, v2
	v_add_u32_e32 v3, v5, v3
	v_cmp_ne_u32_e32 vcc, v4, v3
	s_and_saveexec_b64 s[10:11], vcc
	s_xor_b64 s[10:11], exec, s[10:11]
	s_cbranch_execz .LBB0_187
	s_waitcnt lgkmcnt(0)
	v_add_u32_e32 v5, 1, v2
	v_mul_lo_u32 v5, v5, v1
	v_mov_b32_e32 v1, 0x7400
	global_load_dword v1, v1, s[38:39] sc1
	s_add_u32 s18, s38, 0x7400
	s_addc_u32 s19, s39, 0
	s_waitcnt vmcnt(0)
	v_cmp_lt_u32_e32 vcc, v1, v5
	s_and_saveexec_b64 s[12:13], vcc
	s_cbranch_execz .LBB0_186
	s_add_u32 s14, s38, 0x4200
	s_addc_u32 s15, s39, 0
	s_mov_b32 s46, 1
	s_mov_b64 s[20:21], 0
	v_mov_b32_e32 v1, 0
	s_branch .LBB0_177

.LBB0_179:
	global_load_dword v3, v1, s[18:19] sc1
	s_add_i32 s46, s46, 1
	s_mov_b64 s[26:27], -1
	s_waitcnt vmcnt(0)
	v_cmp_ge_u32_e32 vcc, v3, v5
	s_orn2_b64 s[24:25], vcc, exec
	s_branch .LBB0_176

.LBB0_815:
	s_lshl_b32 s4, s3, 8
	s_add_u32 s4, s40, s4
	s_addc_u32 s5, s41, 0
	v_mov_b32_e32 v2, 0x1000
	v_mov_b32_e32 v4, 1
	global_atomic_add v4, v2, v4, s[4:5] offset:1024 sc0
	v_cvt_f32_u32_e32 v2, v3
	v_sub_u32_e32 v5, 0, v3
	v_rcp_iflag_f32_e32 v2, v2
	s_nop 0
	v_mul_f32_e32 v2, 0x4f7ffffe, v2
	v_cvt_u32_f32_e32 v2, v2
	v_mul_lo_u32 v5, v5, v2
	v_mul_hi_u32 v5, v2, v5
	v_add_u32_e32 v2, v2, v5
	s_waitcnt vmcnt(0)
	v_mul_hi_u32 v2, v4, v2
	v_mul_lo_u32 v5, v2, v3
	v_sub_u32_e32 v5, v4, v5
	v_add_u32_e32 v6, 1, v2
	v_cmp_ge_u32_e32 vcc, v5, v3
	v_add_u32_e32 v4, 1, v4
	s_nop 0
	v_cndmask_b32_e32 v2, v2, v6, vcc
	v_sub_u32_e32 v6, v5, v3
	v_cndmask_b32_e32 v5, v5, v6, vcc
	v_add_u32_e32 v6, 1, v2
	v_cmp_ge_u32_e32 vcc, v5, v3
	s_nop 1
	v_cndmask_b32_e32 v2, v2, v6, vcc
	v_mul_lo_u32 v5, v3, v2
	v_add_u32_e32 v3, v5, v3
	v_cmp_ne_u32_e32 vcc, v4, v3
	s_and_saveexec_b64 s[6:7], vcc
	s_xor_b64 s[6:7], exec, s[6:7]
	s_cbranch_execz .LBB0_829
	s_waitcnt lgkmcnt(0)
	v_add_u32_e32 v5, 1, v2
	v_mul_lo_u32 v5, v5, v1
	v_mov_b32_e32 v1, 0x7400
	global_load_dword v1, v1, s[38:39] sc1
	s_add_u32 s12, s38, 0x7400
	s_addc_u32 s13, s39, 0
	s_waitcnt vmcnt(0)
	v_cmp_lt_u32_e32 vcc, v1, v5
	s_and_saveexec_b64 s[8:9], vcc
	s_cbranch_execz .LBB0_828
	s_add_u32 s10, s38, 0x4200
	s_addc_u32 s11, s39, 0
	s_mov_b32 s26, 1
	s_mov_b64 s[14:15], 0
	v_mov_b32_e32 v1, 0
	s_branch .LBB0_819

.LBB0_821:
	global_load_dword v3, v1, s[12:13] sc1
	s_add_i32 s26, s26, 1
	s_mov_b64 s[22:23], -1
	s_waitcnt vmcnt(0)
	v_cmp_ge_u32_e32 vcc, v3, v5
	s_orn2_b64 s[20:21], vcc, exec
	s_branch .LBB0_818

.LBB0_899:
	s_lshl_b32 s6, s3, 8
	s_add_u32 s6, s40, s6
	s_addc_u32 s7, s41, 0
	v_mov_b32_e32 v2, 0x1000
	v_mov_b32_e32 v4, 1
	global_atomic_add v4, v2, v4, s[6:7] offset:1024 sc0
	v_cvt_f32_u32_e32 v2, v3
	v_sub_u32_e32 v5, 0, v3
	v_rcp_iflag_f32_e32 v2, v2
	s_nop 0
	v_mul_f32_e32 v2, 0x4f7ffffe, v2
	v_cvt_u32_f32_e32 v2, v2
	v_mul_lo_u32 v5, v5, v2
	v_mul_hi_u32 v5, v2, v5
	v_add_u32_e32 v2, v2, v5
	s_waitcnt vmcnt(0)
	v_mul_hi_u32 v2, v4, v2
	v_mul_lo_u32 v5, v2, v3
	v_sub_u32_e32 v5, v4, v5
	v_add_u32_e32 v6, 1, v2
	v_cmp_ge_u32_e32 vcc, v5, v3
	v_add_u32_e32 v4, 1, v4
	s_nop 0
	v_cndmask_b32_e32 v2, v2, v6, vcc
	v_sub_u32_e32 v6, v5, v3
	v_cndmask_b32_e32 v5, v5, v6, vcc
	v_add_u32_e32 v6, 1, v2
	v_cmp_ge_u32_e32 vcc, v5, v3
	s_nop 1
	v_cndmask_b32_e32 v2, v2, v6, vcc
	v_mul_lo_u32 v5, v3, v2
	v_add_u32_e32 v3, v5, v3
	v_cmp_ne_u32_e32 vcc, v4, v3
	s_and_saveexec_b64 s[8:9], vcc
	s_xor_b64 s[8:9], exec, s[8:9]
	s_cbranch_execz .LBB0_913
	s_waitcnt lgkmcnt(0)
	v_add_u32_e32 v5, 1, v2
	v_mul_lo_u32 v5, v5, v1
	v_mov_b32_e32 v1, 0x7400
	global_load_dword v1, v1, s[38:39] sc1
	s_add_u32 s14, s38, 0x7400
	s_addc_u32 s15, s39, 0
	s_waitcnt vmcnt(0)
	v_cmp_lt_u32_e32 vcc, v1, v5
	s_and_saveexec_b64 s[10:11], vcc
	s_cbranch_execz .LBB0_912
	s_add_u32 s12, s38, 0x4200
	s_addc_u32 s13, s39, 0
	s_mov_b32 s26, 1
	s_mov_b64 s[16:17], 0
	v_mov_b32_e32 v1, 0
	s_branch .LBB0_903

.LBB0_905:
	global_load_dword v3, v1, s[14:15] sc1
	s_add_i32 s26, s26, 1
	s_mov_b64 s[22:23], -1
	s_waitcnt vmcnt(0)
	v_cmp_ge_u32_e32 vcc, v3, v5
	s_orn2_b64 s[20:21], vcc, exec
	s_branch .LBB0_902

.LBB0_1150:
	s_lshl_b32 s3, s3, 8
	s_add_u32 s6, s40, s3
	s_addc_u32 s7, s41, 0
	v_mov_b32_e32 v2, 0x1000
	v_mov_b32_e32 v4, 1
	global_atomic_add v4, v2, v4, s[6:7] offset:1024 sc0
	v_cvt_f32_u32_e32 v2, v3
	v_sub_u32_e32 v5, 0, v3
	v_rcp_iflag_f32_e32 v2, v2
	s_nop 0
	v_mul_f32_e32 v2, 0x4f7ffffe, v2
	v_cvt_u32_f32_e32 v2, v2
	v_mul_lo_u32 v5, v5, v2
	v_mul_hi_u32 v5, v2, v5
	v_add_u32_e32 v2, v2, v5
	s_waitcnt vmcnt(0)
	v_mul_hi_u32 v2, v4, v2
	v_mul_lo_u32 v5, v2, v3
	v_sub_u32_e32 v5, v4, v5
	v_add_u32_e32 v6, 1, v2
	v_cmp_ge_u32_e32 vcc, v5, v3
	v_add_u32_e32 v4, 1, v4
	s_nop 0
	v_cndmask_b32_e32 v2, v2, v6, vcc
	v_sub_u32_e32 v6, v5, v3
	v_cndmask_b32_e32 v5, v5, v6, vcc
	v_add_u32_e32 v6, 1, v2
	v_cmp_ge_u32_e32 vcc, v5, v3
	s_nop 1
	v_cndmask_b32_e32 v2, v2, v6, vcc
	v_mul_lo_u32 v5, v3, v2
	v_add_u32_e32 v3, v5, v3
	v_cmp_ne_u32_e32 vcc, v4, v3
	s_and_saveexec_b64 s[8:9], vcc
	s_xor_b64 s[8:9], exec, s[8:9]
	s_cbranch_execz .LBB0_1164
	s_waitcnt lgkmcnt(0)
	v_add_u32_e32 v5, 1, v2
	v_mul_lo_u32 v5, v5, v1
	v_mov_b32_e32 v1, 0x7400
	global_load_dword v1, v1, s[38:39] sc1
	s_add_u32 s14, s38, 0x7400
	s_addc_u32 s15, s39, 0
	s_waitcnt vmcnt(0)
	v_cmp_lt_u32_e32 vcc, v1, v5
	s_and_saveexec_b64 s[10:11], vcc
	s_cbranch_execz .LBB0_1163
	s_add_u32 s12, s38, 0x4200
	s_addc_u32 s13, s39, 0
	s_mov_b32 s3, 1
	s_mov_b64 s[16:17], 0
	v_mov_b32_e32 v1, 0
	s_branch .LBB0_1154

.LBB0_1156:
	global_load_dword v3, v1, s[14:15] sc1
	s_add_i32 s3, s3, 1
	s_mov_b64 s[22:23], -1
	s_waitcnt vmcnt(0)
	v_cmp_ge_u32_e32 vcc, v3, v5
	s_orn2_b64 s[20:21], vcc, exec
	s_branch .LBB0_1153
